# ffn_up: odd-rank workgroups run the half-tile pass before their full tiles (staggers epilogue store bursts between two groups)
# baseline (speedup 1.0000x reference)
; #define LAS __attribute__((address_space(3)))
; #define RTID opaque_tid()
; #define ZERO_ACC8(acc, NJ_)                             \
;   _Pragma("unroll") for (int i_ = 0; i_ < 8; ++i_)      \
;   _Pragma("unroll") for (int j_ = 0; j_ < (NJ_); ++j_) { acc[i_][j_] = (f32x4){0.f, 0.f, 0.f, 0.f}; }
; __device__ __forceinline__ void phase_ffn_up(const Params& p, const u16* Wgu, u16* smem, volatile LAS unsigned* vb_) {
;   const u16* H = (const u16*)(p.ws + OFF_H);
;   u16* act = (u16*)(p.ws + OFF_ACT);
;   const int tid = RTID;
;   const int lane = tid & 63, wave = tid >> 6;
;   const int wm = wave >> 2, wn = wave & 3;
;   const int vb = real_vb(vb_);
;   const int step = gridDim.x >> 3;
;   G8REGS_DECL;
;   bool pre = false;
;   for (int lt = vb >> 3; lt < 8 * 20; lt += step) {
;     const int nt = lt >> 3, mt = (vb & 7) * 8 + (lt & 7);
;     const int ltn = (lt + step < 8 * 20) ? lt + step : lt;
;     f32x4 acc[8][4];
;     ZERO_ACC8(acc, 4);
;     gemm8<8, 4>(acc, G8REGS_ARGS, pre, H, 1024, Wgu, 1024, 0, 1024, mt * 256, nt * 256,
;                 ((vb & 7) * 8 + (ltn & 7)) * 256, (ltn >> 3) * 256, 0, smem, tid);
;     ...
;   for (int lt = vb >> 3; lt < 8 * 4; lt += step) {
;     const int hn = lt >> 3, mt = (vb & 7) * 8 + (lt & 7);
;     f32x4 acc[8][2];
;     ZERO_ACC8(acc, 2);
;     G8REGS_DECL;
;     R_b2 = R_b3 = make_uint4(0u, 0u, 0u, 0u);
;     gemm8<8, 2>(acc, G8REGS_ARGS, false, H, 1024, Wgu, 1024, 0, 1024, mt * 256, 5120 + hn * 128, mt * 256, 5120 + hn * 128, 0, smem, tid);
.LBB0_595:
	s_nop 0
	v_readlane_b32 s0, v255, 0
	v_readlane_b32 s1, v255, 1
	s_and_b64 vcc, exec, s[0:1]
	s_cbranch_vccz .LBB0_608
	s_mov_b32 s99, 0
.Lffn_again:
	s_waitcnt vmcnt(15)
	v_mov_b32_e32 v2, v175
	ds_read_b32 v0, v230
	s_cmp_eq_u32 s82, 0
	s_cselect_b32 s0, 0, 0x1080000
	s_add_u32 s0, s72, s0
	s_addc_u32 s1, s73, 0
	s_waitcnt lgkmcnt(0)
	v_readfirstlane_b32 s37, v0
	s_ashr_i32 s36, s37, 3
	v_ashrrev_i32_e32 v176, 3, v2
	v_lshlrev_b32_e32 v3, 4, v2
	v_lshrrev_b32_e32 v4, 4, v2
	v_and_b32_e32 v5, 7, v2
	v_lshrrev_b32_e32 v180, 1, v2
	v_and_b32_e32 v179, 15, v2
	s_waitcnt vmcnt(13)
	v_lshrrev_b32_e32 v6, 2, v2
	s_mov_b32 s10, 0x1ffff80
	v_ashrrev_i32_e32 v177, 8, v2
	v_bfe_u32 v178, v2, 6, 2
	s_cmpk_gt_i32 s36, 0x9f
	v_and_b32_e32 v0, 0x70, v3
	v_xor_b32_e32 v184, v176, v2
	v_bitop3_b32 v182, v4, v5, 3 bitop3:0x6c
	v_and_or_b32 v183, v180, s10, v179
	v_and_b32_e32 v181, 12, v6
	s_cbranch_scc1 .LBB0_603
	s_cmp_lg_u32 s99, 0
	s_cbranch_scc1 .Lffn_full
	s_bitcmp1_b32 s37, 3
	s_cbranch_scc0 .Lffn_full
	s_mov_b32 s99, 1
	s_branch .LBB0_603
.Lffn_full:
	v_lshlrev_b32_e32 v4, 4, v184
	s_lshl_b32 s10, s37, 3
	v_and_b32_e32 v4, 0x70, v4
	s_and_b32 s38, s10, 56
	v_readlane_b32 s10, v252, 38
	v_lshl_or_b32 v185, v176, 7, v4
	v_lshlrev_b32_e32 v4, 3, v182
	v_readlane_b32 s11, v252, 39
	v_xor_b32_e32 v5, 32, v4
	v_lshlrev_b32_e32 v6, 7, v2
	v_lshl_add_u64 v[162:163], s[10:11], 0, v[0:1]
	v_sub_u32_e32 v5, v5, v4
	v_lshlrev_b32_e32 v4, 4, v182
	v_and_b32_e32 v6, 0x6780, v6
	s_mov_b32 s10, 0x10000
	v_lshl_or_b32 v187, v183, 7, v4
	v_or3_b32 v188, v6, v4, s10
	v_lshlrev_b32_e32 v4, 1, v179
	v_lshl_or_b32 v8, v177, 7, v181
	v_lshl_or_b32 v4, v178, 6, v4
	v_and_b32_e32 v6, 0xf0, v3
	v_mov_b32_e32 v7, v1
	s_movk_i32 s12, 0x110
	v_lshl_add_u64 v[166:167], s[78:79], 0, v[6:7]
	v_ashrrev_i32_e32 v189, 4, v2
	v_mad_u64_u32 v[168:169], s[10:11], v8, s12, v[4:5]
	v_add_u32_e32 v4, 0x200, v2
	v_add_u32_e32 v7, 0x400, v2
	v_add_u32_e32 v8, 0x600, v2
	v_add_u32_e32 v9, 0x800, v2
	s_waitcnt vmcnt(12)
	v_add_u32_e32 v10, 0xa00, v2
	v_add_u32_e32 v11, 0xc00, v2
	v_add_u32_e32 v2, 0xe00, v2
	v_ashrrev_i32_e32 v169, 4, v4
	v_ashrrev_i32_e32 v190, 4, v7
	v_ashrrev_i32_e32 v191, 4, v8
	v_ashrrev_i32_e32 v192, 4, v9
	v_ashrrev_i32_e32 v193, 4, v10
	v_ashrrev_i32_e32 v194, 4, v11
	v_ashrrev_i32_e32 v195, 4, v2
	v_mul_lo_u32 v3, v189, s12
	v_mul_lo_u32 v4, v169, s12
	v_mul_lo_u32 v7, v190, s12
	v_mul_lo_u32 v8, v191, s12
	v_mul_lo_u32 v9, v192, s12
	v_mul_lo_u32 v10, v193, s12
	v_mul_lo_u32 v11, v194, s12
	v_mul_lo_u32 v2, v195, s12
	v_lshl_add_u64 v[164:165], s[0:1], 0, v[0:1]
	v_add_u32_e32 v186, 0x10000, v185
	s_mov_b64 s[12:13], 0
	v_lshlrev_b32_e32 v196, 1, v5
	v_add_u32_e32 v197, v6, v3
	v_add_u32_e32 v198, v6, v4
	v_add_u32_e32 v199, v6, v7
	v_add_u32_e32 v200, v6, v8
	v_add_u32_e32 v204, v6, v9
	v_add_u32_e32 v205, v6, v10
	v_add_u32_e32 v206, v6, v11
	v_add_u32_e32 v207, v6, v2
	s_mov_b32 s20, s36
	v_bfe_u32 v169, v175, 3, 3
	v_and_b32_e32 v194, 7, v175
	v_lshlrev_b32_e32 v194, 4, v194
	v_lshl_add_u32 v169, v169, 11, v194
	v_add_u32_e32 v194, 0x20000, v169
	v_add_u32_e32 v195, 0x40000, v169
	v_add_u32_e32 v198, 0x60000, v169

; #define ZERO_ACC8(acc, NJ_)                             \
;   _Pragma("unroll") for (int i_ = 0; i_ < 8; ++i_)      \
;   _Pragma("unroll") for (int j_ = 0; j_ < (NJ_); ++j_) { acc[i_][j_] = (f32x4){0.f, 0.f, 0.f, 0.f}; }
; __device__ __forceinline__ void phase_ffn_up(const Params& p, const u16* Wgu, u16* smem, volatile LAS unsigned* vb_) {
;     ...
;   for (int lt = vb >> 3; lt < 8 * 4; lt += step) {
;     const int hn = lt >> 3, mt = (vb & 7) * 8 + (lt & 7);
;     f32x4 acc[8][2];
;     ZERO_ACC8(acc, 2);
;     G8REGS_DECL;
;     R_b2 = R_b3 = make_uint4(0u, 0u, 0u, 0u);
;     gemm8<8, 2>(acc, G8REGS_ARGS, false, H, 1024, Wgu, 1024, 0, 1024, mt * 256, 5120 + hn * 128, mt * 256, 5120 + hn * 128, 0, smem, tid);
.LBB0_603:
	s_waitcnt vmcnt(0)
	s_cmp_eq_u32 s99, 2
	s_cbranch_scc1 .LBB0_608
	s_cmp_gt_i32 s36, 31
	s_cbranch_scc1 .Lffn_halfdone
	v_readlane_b32 s12, v252, 38
	v_readlane_b32 s13, v252, 39
	s_waitcnt vmcnt(15)
	v_lshlrev_b32_e32 v2, 3, v182
	v_lshl_add_u64 v[92:93], s[0:1], 0, v[0:1]
	v_lshl_add_u64 v[90:91], s[12:13], 0, v[0:1]
	v_lshlrev_b32_e32 v0, 4, v184
	v_xor_b32_e32 v3, 32, v2
	v_and_or_b32 v4, v180, s9, v179
	v_and_b32_e32 v0, 0x70, v0
	v_sub_u32_e32 v2, v3, v2
	v_lshlrev_b32_e32 v3, 4, v182
	v_lshlrev_b32_e32 v4, 7, v4
	s_mov_b32 s0, 0x10000
	s_lshl_b32 s10, s37, 3
	v_lshl_or_b32 v0, v176, 7, v0
	v_lshl_or_b32 v100, v183, 7, v3
	v_or3_b32 v101, v4, v3, s0
	v_lshlrev_b32_e32 v3, 4, v178
	s_movk_i32 s0, 0xa00
	s_and_b32 s10, s10, 56
	v_add_u32_e32 v98, 0x1400, v176
	v_add_u32_e32 v99, 0x10000, v0
	v_lshl_or_b32 v102, v177, 7, v181
	v_or3_b32 v103, v3, v179, s0
	v_lshlrev_b32_e32 v104, 1, v2

; #define ZERO_ACC8(acc, NJ_)                             \
;   _Pragma("unroll") for (int i_ = 0; i_ < 8; ++i_)      \
;   _Pragma("unroll") for (int j_ = 0; j_ < (NJ_); ++j_) { acc[i_][j_] = (f32x4){0.f, 0.f, 0.f, 0.f}; }
; __device__ __forceinline__ void phase_ffn_up(const Params& p, const u16* Wgu, u16* smem, volatile LAS unsigned* vb_) {
;     ...
;   for (int lt = vb >> 3; lt < 8 * 4; lt += step) {
;     const int hn = lt >> 3, mt = (vb & 7) * 8 + (lt & 7);
;     f32x4 acc[8][2];
;     ZERO_ACC8(acc, 2);
;     G8REGS_DECL;
;     R_b2 = R_b3 = make_uint4(0u, 0u, 0u, 0u);
;     gemm8<8, 2>(acc, G8REGS_ARGS, false, H, 1024, Wgu, 1024, 0, 1024, mt * 256, 5120 + hn * 128, mt * 256, 5120 + hn * 128, 0, smem, tid);
.Lffn_halfdone:
	s_cmp_eq_u32 s99, 1
	s_cbranch_scc0 .LBB0_608
	s_mov_b32 s99, 2
	s_waitcnt vmcnt(0)
	s_branch .Lffn_again
